# diff-attn tile loop: LDS-DMA source addresses as SGPR base + loop-invariant 32-bit lane offsets (removes nine 64-bit VALU adds per wave per tile)
# speedup vs baseline: 1.0068x; 1.0039x over previous
; #define LAS __attribute__((address_space(3)))
; __device__ __forceinline__ int v_rd_base(int lane) { return ((lane & 3) << 3) | (((lane >> 2) & 3) << 6) | (((lane >> 4) & 1) << 5) | (((lane >> 5) & 1) << 8); }
; __device__ __forceinline__ int swap23(int k) { return (k & ~0xC) | ((k & 4) << 1) | ((k & 8) >> 1); }
; #define A3_BAR() do { asm volatile("s_waitcnt vmcnt(0) lgkmcnt(0)" ::: "memory"); __builtin_amdgcn_s_barrier(); asm volatile("" ::: "memory"); } while (0)
; #define lane lane_id()
; __device__ __forceinline__ void attn_block3(const BlockRef& cur, char* lds, const int wid) {
;     const int lane = lane_id(), r32 = lane & 31, hi = lane >> 5;
;     const int NT = (cur.P0 + QB - 1) / KVBLK + 1;
;     const int qlo = cur.P0 + wid * QBLK, qm = qlo + r32 - 4 * hi;
;     char* V_lds = lds + A3_V; char* K_lds = lds + A3_K;
;     float* ws = (float*)(lds + A3_WS) + wid * 64; float* li_l = ws, * al_l = ws + 32;
;     const float* tb = cur.tb;
;     unsigned kgo[2], vgo[2];
; #pragma unroll
;     for (int i = 0; i < 2; ++i) { const int pc = 2 * wid + i;
;         const int row = 4 * pc + (lane >> 4), c = (lane & 15) ^ (row & 7); kgo[i] = (unsigned)(row * 256 + c * 16);
;         const int sub = 2 * pc + (lane >> 5), kk = (sub >> 2) * 8 + ((lane & 31) >> 2), k = swap23(kk), cc = (sub & 3) * 32 + (lane & 3) * 8; vgo[i] = (unsigned)(k * 256 + cc * 2); }
;     bf16x8 qr[8];
; #pragma unroll
;     for (int d0 = 0; d0 < 8; ++d0) qr[d0] = load8(cur.Q + (size_t)(wid * QBLK + r32) * D + d0 * 16 + hi * 8);
;     LAS unsigned char* ldsl = (LAS unsigned char*)lds;
;     const char* Kg = (const char*)cur.K; const char* Vg = (const char*)cur.V; const char* Vg2 = (const char*)cur.V2;
;     ...
;     A3_DMA(0);
;     A3_BAR();
;     float m_reg = -1e30f, l_reg = 0; f32x16 o[4] = {}, o2[4] = {};
;     const int vbase = (int)(uintptr_t)V_lds + v_rd_base(lane);
.LBB0_447:
	s_or_b64 exec, exec, s[4:5]
	s_cmp_lg_u32 s77, -1
	s_cselect_b32 s4, s77, 0
	s_cselect_b32 s5, s11, 0
	v_mov_b32_e32 v2, s4
	v_mov_b32_e32 v3, s5
	s_waitcnt lgkmcnt(0)
	s_barrier
	flat_load_dword v0, v[2:3] sc0 sc1
	s_waitcnt vmcnt(0)
	s_mov_b64 s[4:5], -1
	s_waitcnt lgkmcnt(0)
	v_readfirstlane_b32 s6, v0
	s_cmp_gt_u32 s6, 63
	s_cbranch_scc1 .LBB0_442
	s_sub_i32 s44, 63, s6
	s_lshl_b32 s4, s44, 16
	v_mbcnt_lo_u32_b32 v239, -1, 0
	v_mbcnt_hi_u32_b32 v239, -1, v239
	s_or_b32 s4, s4, s78
	v_bfe_u32 v9, v239, 4, 2
	v_and_b32_e32 v0, 15, v239
	v_and_b32_e32 v238, 31, v239
	v_bitop3_b32 v0, v9, v0, 4 bitop3:0x36
	s_add_u32 s4, s34, s4
	v_bitop3_b32 v5, v9, v239, 15 bitop3:0x78
	v_lshlrev_b32_e32 v14, 4, v0
	v_or_b32_e32 v0, s39, v238
	s_addc_u32 s5, s35, 0
	v_and_b32_e32 v8, 63, v239
	v_bfe_u32 v2, v239, 2, 3
	v_or_b32_e32 v4, s15, v9
	v_lshlrev_b32_e32 v13, 4, v5
	v_bfe_u32 v16, v239, 5, 1
	v_lshlrev_b32_e32 v0, 8, v0
	v_bitop3_b32 v10, v2, 51, s15 bitop3:0xc8
	v_lshrrev_b32_e32 v2, 1, v239
	v_and_b32_e32 v3, 32, v239
	v_lshlrev_b32_e32 v12, 3, v8
	v_lshl_or_b32 v6, v4, 8, v13
	v_lshl_add_u64 v[4:5], s[4:5], 0, v[0:1]
	v_lshlrev_b32_e32 v0, 4, v16
	v_and_b32_e32 v11, 8, v2
	v_and_or_b32 v3, v12, 24, v3
	v_lshl_add_u64 v[4:5], v[4:5], 0, v[0:1]
	v_or3_b32 v2, v11, v10, s81
	v_lshlrev_b32_e32 v3, 1, v3
	global_load_dwordx4 v[192:195], v[4:5], off
	global_load_dwordx4 v[196:199], v[4:5], off offset:32
	global_load_dwordx4 v[200:203], v[4:5], off offset:64
	global_load_dwordx4 v[204:207], v[4:5], off offset:96
	global_load_dwordx4 v[208:211], v[4:5], off offset:128
	global_load_dwordx4 v[212:215], v[4:5], off offset:160
	global_load_dwordx4 v[216:219], v[4:5], off offset:192
	global_load_dwordx4 v[220:223], v[4:5], off offset:224
	s_mov_b32 m0, s83
	v_lshl_or_b32 v2, v2, 8, v3
	v_or_b32_e32 v3, 4, v9
	v_or_b32_e32 v3, s15, v3
	global_load_lds_dwordx4 v6, s[56:57]
	s_mov_b32 m0, s82
	v_lshl_or_b32 v15, v3, 8, v14
	v_mov_b32_e32 v3, v1
	global_load_lds_dwordx4 v2, s[58:59]
	s_add_i32 m0, s82, 0x4000
	v_lshl_add_u64 v[4:5], s[58:59], 0, v[2:3]
	global_load_lds_dwordx4 v2, s[62:63]
	s_add_i32 m0, s82, 0x10400
	v_lshl_add_u64 v[6:7], s[62:63], 0, v[2:3]
	global_load_lds_dwordx4 v15, s[56:57]
	v_lshl_add_u64 v[2:3], v[4:5], 0, s[46:47]
	s_add_i32 m0, s82, 0x400
	s_lshl_b32 s7, s44, 8
	global_load_lds_dwordx4 v[2:3], off
	v_lshl_add_u64 v[2:3], v[6:7], 0, s[46:47]
	s_add_i32 m0, s82, 0x4400
	s_lshl_b32 s4, s44, 2
	global_load_lds_dwordx4 v[2:3], off
	s_or_b32 s79, s7, s39
	s_or_b32 s87, s4, 3
	v_lshlrev_b32_e32 v3, 4, v239
	s_movk_i32 s4, 0x70
	v_and_b32_e32 v2, 0x118, v12
	v_and_b32_e32 v4, 0xc0, v3
	v_and_b32_e32 v5, 0x70, v3
	v_bitop3_b32 v242, v0, v3, s4 bitop3:0x78
	v_lshlrev_b32_e32 v3, 1, v239
	s_cmp_lg_u32 0, -1
	s_movk_i32 s4, 0x60
	v_and_or_b32 v2, v3, 32, v2
	s_cselect_b32 s7, 0, 0
	v_bitop3_b32 v243, v0, v5, 32 bitop3:0x36
	v_bitop3_b32 v244, v0, v5, 64 bitop3:0x36
	v_bitop3_b32 v245, v0, v5, s4 bitop3:0x36
	v_lshlrev_b32_e32 v5, 2, v238
	v_add3_u32 v246, v4, s7, v2
	s_lshl_b32 s7, s6, 2
	v_add_u32_e32 v2, s81, v10
	v_and_b32_e32 v4, 3, v239
	v_add_u32_e32 v237, s1, v0
	s_sub_i32 s88, 0x100, s7
	v_add_lshl_u32 v2, v2, v11, 8
	v_and_b32_e32 v3, 64, v3
	v_lshlrev_b32_e32 v4, 4, v4
	v_sub_u32_e32 v0, v5, v0
	s_lshl_b32 s7, s6, 10
	v_or3_b32 v2, v2, v3, v4
	v_mov_b32_e32 v3, v1
	v_lshlrev_b32_e32 v4, 8, v9
	v_subrev_u32_e32 v0, s7, v0
	v_lshlrev_b32_e32 v236, 2, v16
	v_mov_b32_e32 v224, v2
	v_add_u32_e32 v225, 0x80, v2
	v_add3_u32 v2, s86, v4, v13
	v_add_u32_e32 v247, s75, v0
	v_add_u32_e32 v0, s76, v238
	s_waitcnt vmcnt(0) lgkmcnt(0)
	s_barrier
	v_mov_b32_e32 v228, v2
	v_add3_u32 v2, s74, v4, v14
	v_sub_u32_e32 v0, v0, v236
	s_lshl_b32 s6, s6, 8
	v_mov_b32_e32 v14, v1
	v_mov_b32_e32 v15, v1
	v_cmp_gt_u32_e64 s[4:5], 32, v8
	v_add_u32_e32 v241, s1, v5
	v_mov_b32_e32 v230, v2
	v_subrev_u32_e32 v248, s6, v0
	v_mov_b32_e32 v0, v1
	v_mov_b32_e32 v2, v1
	v_mov_b32_e32 v4, v1
	v_mov_b32_e32 v5, v1
	v_mov_b32_e32 v6, v1
	v_mov_b32_e32 v7, v1
	v_mov_b32_e32 v8, v1
	v_mov_b32_e32 v9, v1
	v_mov_b32_e32 v10, v1
	v_mov_b32_e32 v11, v1
	v_mov_b32_e32 v12, v1
	v_mov_b32_e32 v13, v1
	v_mov_b64_e32 v[30:31], v[14:15]
	v_mov_b64_e32 v[62:63], v[14:15]
	v_mov_b64_e32 v[94:95], v[14:15]
	v_mov_b64_e32 v[126:127], v[14:15]
	v_mov_b64_e32 v[46:47], v[14:15]
	v_mov_b64_e32 v[78:79], v[14:15]
	v_mov_b64_e32 v[110:111], v[14:15]
	v_mov_b64_e32 v[142:143], v[14:15]
	v_lshlrev_b32_e32 v240, 8, v238
	s_mov_b32 s93, 0
	v_mov_b32_e32 v250, 0
	v_mov_b32_e32 v249, 0xf149f2ca
	s_movk_i32 s90, 0xb0
	s_add_u32 s68, s18, s66
	s_addc_u32 s69, s19, s67
	s_add_u32 s98, s18, s64
	s_addc_u32 s99, s19, s65
	s_add_u32 s98, s98, s48
	s_addc_u32 s99, s99, s49
	s_add_u32 s100, s18, s60
	s_addc_u32 s101, s19, s61
	s_add_u32 s100, s100, s48
	s_addc_u32 s101, s101, s49
	v_mov_b64_e32 v[28:29], v[12:13]
	v_mov_b64_e32 v[26:27], v[10:11]
	v_mov_b64_e32 v[24:25], v[8:9]
	v_mov_b64_e32 v[22:23], v[6:7]
	v_mov_b64_e32 v[20:21], v[4:5]
	v_mov_b64_e32 v[18:19], v[2:3]
	v_mov_b64_e32 v[16:17], v[0:1]
	v_mov_b64_e32 v[60:61], v[12:13]
	v_mov_b64_e32 v[58:59], v[10:11]
	v_mov_b64_e32 v[56:57], v[8:9]
	v_mov_b64_e32 v[54:55], v[6:7]
	v_mov_b64_e32 v[52:53], v[4:5]
	v_mov_b64_e32 v[50:51], v[2:3]
	v_mov_b64_e32 v[48:49], v[0:1]
	v_mov_b64_e32 v[92:93], v[12:13]
	v_mov_b64_e32 v[90:91], v[10:11]
	v_mov_b64_e32 v[88:89], v[8:9]
	v_mov_b64_e32 v[86:87], v[6:7]
	v_mov_b64_e32 v[84:85], v[4:5]
	v_mov_b64_e32 v[82:83], v[2:3]
	v_mov_b64_e32 v[80:81], v[0:1]
	v_mov_b64_e32 v[124:125], v[12:13]
	v_mov_b64_e32 v[122:123], v[10:11]
	v_mov_b64_e32 v[120:121], v[8:9]
	v_mov_b64_e32 v[118:119], v[6:7]
	v_mov_b64_e32 v[116:117], v[4:5]
	v_mov_b64_e32 v[114:115], v[2:3]
	v_mov_b64_e32 v[112:113], v[0:1]
	v_mov_b64_e32 v[44:45], v[12:13]
	v_mov_b64_e32 v[42:43], v[10:11]
	v_mov_b64_e32 v[40:41], v[8:9]
	v_mov_b64_e32 v[38:39], v[6:7]
	v_mov_b64_e32 v[36:37], v[4:5]
	v_mov_b64_e32 v[34:35], v[2:3]
	v_mov_b64_e32 v[32:33], v[0:1]
	v_mov_b64_e32 v[76:77], v[12:13]
	v_mov_b64_e32 v[74:75], v[10:11]
	v_mov_b64_e32 v[72:73], v[8:9]
	v_mov_b64_e32 v[70:71], v[6:7]
	v_mov_b64_e32 v[68:69], v[4:5]
	v_mov_b64_e32 v[66:67], v[2:3]
	v_mov_b64_e32 v[64:65], v[0:1]
	v_mov_b64_e32 v[108:109], v[12:13]
	v_mov_b64_e32 v[106:107], v[10:11]
	v_mov_b64_e32 v[104:105], v[8:9]
	v_mov_b64_e32 v[102:103], v[6:7]
	v_mov_b64_e32 v[100:101], v[4:5]
	v_mov_b64_e32 v[98:99], v[2:3]
	v_mov_b64_e32 v[96:97], v[0:1]
	v_mov_b64_e32 v[140:141], v[12:13]
	v_mov_b64_e32 v[138:139], v[10:11]
	v_mov_b64_e32 v[136:137], v[8:9]
	v_mov_b64_e32 v[134:135], v[6:7]
	v_mov_b64_e32 v[132:133], v[4:5]
	v_mov_b64_e32 v[130:131], v[2:3]
	v_mov_b64_e32 v[128:129], v[0:1]
	s_waitcnt vmcnt(0)
; #define SBAR() __builtin_amdgcn_sched_barrier(0)
; __device__ __forceinline__ void attn_block3(const BlockRef& cur, char* lds, const int wid) {
;     ...
;     for (int t = 0; t < NT; ++t) {
;         f32x16 p0, p1; float mn, alpha; bf16x8 pa0, pa1, pa2, pa3;
;         const int kb = t * KVBLK;
;         qkt<0, false>(p0, p1, K_lds + (t & 1) * SHM_K, r32, hi, qr, true);
;         SBAR(); if (t + 1 < NT) A3_DMA(t + 1);
.LBB0_449:
	s_and_b32 s95, s93, 1
	s_lshl_b32 s7, s95, 14
	s_add_i32 s7, s7, 0
	s_add_i32 s7, s7, 0x10000
	v_add3_u32 v0, s7, v242, v240
	ds_read_b128 v[2:5], v0
	ds_read_b128 v[10:13], v0 offset:8192
	v_add3_u32 v6, s7, v243, v240
	ds_read_b128 v[176:179], v6
	ds_read_b128 v[180:183], v6 offset:8192
	v_add3_u32 v7, s7, v244, v240
	ds_read_b128 v[184:187], v7
	ds_read_b128 v[188:191], v7 offset:8192
	s_mov_b32 s6, s93
	s_waitcnt lgkmcnt(5)
	v_mfma_f32_32x32x16_bf16 v[160:175], v[2:5], v[192:195], 0
	v_add3_u32 v8, s7, v245, v240
	ds_read_b128 v[2:5], v8
	s_waitcnt lgkmcnt(5)
	v_mfma_f32_32x32x16_bf16 v[144:159], v[10:13], v[192:195], 0
	ds_read_b128 v[10:13], v8 offset:8192
	s_waitcnt lgkmcnt(5)
	v_mfma_f32_32x32x16_bf16 v[160:175], v[176:179], v[196:199], v[160:175]
	ds_read_b128 v[176:179], v0 offset:128
	s_waitcnt lgkmcnt(5)
	v_mfma_f32_32x32x16_bf16 v[144:159], v[180:183], v[196:199], v[144:159]
	ds_read_b128 v[180:183], v0 offset:8320
	s_waitcnt lgkmcnt(5)
	v_mfma_f32_32x32x16_bf16 v[160:175], v[184:187], v[200:203], v[160:175]
	ds_read_b128 v[184:187], v6 offset:128
	s_waitcnt lgkmcnt(5)
	v_mfma_f32_32x32x16_bf16 v[144:159], v[188:191], v[200:203], v[144:159]
	ds_read_b128 v[188:191], v6 offset:8320
	s_waitcnt lgkmcnt(5)
	v_mfma_f32_32x32x16_bf16 v[160:175], v[2:5], v[204:207], v[160:175]
	ds_read_b128 v[2:5], v7 offset:128
	s_waitcnt lgkmcnt(5)
	v_mfma_f32_32x32x16_bf16 v[144:159], v[10:13], v[204:207], v[144:159]
	ds_read_b128 v[10:13], v7 offset:8320
	s_waitcnt lgkmcnt(5)
	v_mfma_f32_32x32x16_bf16 v[160:175], v[176:179], v[208:211], v[160:175]
	ds_read_b128 v[176:179], v8 offset:128
	s_waitcnt lgkmcnt(5)
	v_mfma_f32_32x32x16_bf16 v[144:159], v[180:183], v[208:211], v[144:159]
	ds_read_b128 v[180:183], v8 offset:8320
	s_waitcnt lgkmcnt(5)
	v_mfma_f32_32x32x16_bf16 v[160:175], v[184:187], v[212:215], v[160:175]
	s_waitcnt lgkmcnt(4)
	v_mfma_f32_32x32x16_bf16 v[144:159], v[188:191], v[212:215], v[144:159]
	s_waitcnt lgkmcnt(3)
	v_mfma_f32_32x32x16_bf16 v[160:175], v[2:5], v[216:219], v[160:175]
	s_waitcnt lgkmcnt(2)
	v_mfma_f32_32x32x16_bf16 v[144:159], v[10:13], v[216:219], v[144:159]
	s_waitcnt lgkmcnt(1)
	v_mfma_f32_32x32x16_bf16 v[160:175], v[176:179], v[220:223], v[160:175]
	s_waitcnt lgkmcnt(0)
	v_mfma_f32_32x32x16_bf16 v[144:159], v[180:183], v[220:223], v[144:159]
	s_add_i32 s93, s93, 1
	s_cmp_ge_u32 s6, s87
	s_cbranch_scc1 .LBB0_451
	s_and_b32 s6, s93, 1
	s_lshl_b32 s7, s6, 14
	s_add_i32 s7, s83, s7
	s_lshl_b32 s6, s6, 15
	s_mov_b32 m0, s7
	s_add_i32 s6, s82, s6
	global_load_lds_dwordx4 v228, s[68:69]
	s_mov_b32 m0, s6
	s_add_i32 s20, s6, 0x4000
	global_load_lds_dwordx4 v224, s[98:99]
	s_mov_b32 m0, s20
	s_nop 0
	global_load_lds_dwordx4 v224, s[100:101]
	s_add_i32 m0, s7, 0x400
	s_nop 0
	global_load_lds_dwordx4 v230, s[68:69]
	s_add_i32 m0, s6, 0x400
	s_nop 0
	global_load_lds_dwordx4 v225, s[98:99]
	s_add_i32 m0, s6, 0x4400
	s_nop 0
	global_load_lds_dwordx4 v225, s[100:101]

; __device__ __forceinline__ void partialSM(f32x16& p0, f32x16& p1, float& m_reg, float& mn, float& alpha) {
;     float pmax = p0[0];
; #pragma unroll
;     for (int r = 1; r < 16; ++r) pmax = fmaxf(pmax, p0[r]);
; #pragma unroll
;     for (int r = 0; r < 16; ++r) pmax = fmaxf(pmax, p1[r]);
;     { auto rr = __builtin_amdgcn_permlane32_swap(__float_as_uint(pmax), __float_as_uint(pmax), false, false);
;       pmax = fmaxf(__uint_as_float(rr[0]), __uint_as_float(rr[1])); }
;     constexpr float C2 = 1.4426950408889634f * SM_SCALE;
;     if (__builtin_expect(__all((pmax - m_reg) * SM_SCALE <= THR), 1)) { mn = m_reg; alpha = 1.f; }
;     else { mn = fmaxf(m_reg, pmax); alpha = __builtin_amdgcn_exp2f((m_reg - mn) * C2); m_reg = mn; }
;     const float mnL = -mn * C2;
; #pragma unroll
;     for (int r = 0; r < 16; ++r) p0[r] = fmaf(p0[r], C2, mnL);
; #pragma unroll
;     for (int r = 0; r < 16; ++r) p1[r] = fmaf(p1[r], C2, mnL);
; #pragma unroll
;     for (int r = 0; r < 16; ++r) p0[r] = __builtin_amdgcn_exp2f(p0[r]);
; }
; __device__ __forceinline__ void finishSM(f32x16& p0, f32x16& p1, float alpha, float& l_reg, bf16x8& pa0, bf16x8& pa1, bf16x8& pa2, bf16x8& pa3) {
; #pragma unroll
;     for (int r = 0; r < 16; ++r) p1[r] = __builtin_amdgcn_exp2f(p1[r]);
;     float ps = 0;
; #pragma unroll
;     for (int r = 0; r < 16; ++r) ps += p0[r];
; #pragma unroll
;     for (int r = 0; r < 16; ++r) ps += p1[r];
;     { auto rr = __builtin_amdgcn_permlane32_swap(__float_as_uint(ps), __float_as_uint(ps), false, false);
;       ps = __uint_as_float(rr[0]) + __uint_as_float(rr[1]); }
;     l_reg = l_reg * alpha + ps;
;     PK4(p0, 0, pa0); PK4(p0, 8, pa1); PK4(p1, 0, pa2); PK4(p1, 8, pa3);
; }
; __device__ __forceinline__ void pv_tile2(f32x16* o, f32x16* o2, int vb0, bf16x8 pa0, bf16x8 pa1, bf16x8 pa2, bf16x8 pa3) {
.LBB0_489:
	v_cndmask_b32_e64 v249, v14, v249, s[6:7]
	v_mul_f32_e32 v2, 0xbe0293ee, v249
	v_fmamk_f32 v3, v160, 0x3e0293ee, v2
	v_fmamk_f32 v4, v161, 0x3e0293ee, v2
	v_exp_f32_e32 v3, v3
	v_fmamk_f32 v5, v162, 0x3e0293ee, v2
	v_exp_f32_e32 v4, v4
	v_fmamk_f32 v6, v163, 0x3e0293ee, v2
	v_exp_f32_e32 v5, v5
	v_fmamk_f32 v7, v164, 0x3e0293ee, v2
	v_fmamk_f32 v8, v165, 0x3e0293ee, v2
	v_fmamk_f32 v9, v166, 0x3e0293ee, v2
	v_fmamk_f32 v10, v167, 0x3e0293ee, v2
	v_fmamk_f32 v11, v168, 0x3e0293ee, v2
	v_fmamk_f32 v12, v169, 0x3e0293ee, v2
	v_fmamk_f32 v13, v170, 0x3e0293ee, v2
	v_fmamk_f32 v14, v171, 0x3e0293ee, v2
	v_fmamk_f32 v15, v172, 0x3e0293ee, v2
	v_fmamk_f32 v160, v173, 0x3e0293ee, v2
	v_fmamk_f32 v161, v174, 0x3e0293ee, v2
	v_fmamk_f32 v162, v175, 0x3e0293ee, v2
	v_fmamk_f32 v144, v144, 0x3e0293ee, v2
	v_fmamk_f32 v145, v145, 0x3e0293ee, v2
	v_fmamk_f32 v146, v146, 0x3e0293ee, v2
	v_fmamk_f32 v147, v147, 0x3e0293ee, v2
	v_fmamk_f32 v148, v148, 0x3e0293ee, v2
	v_fmamk_f32 v149, v149, 0x3e0293ee, v2
	v_fmamk_f32 v150, v150, 0x3e0293ee, v2
	v_fmamk_f32 v151, v151, 0x3e0293ee, v2
	v_fmamk_f32 v152, v152, 0x3e0293ee, v2
	v_fmamk_f32 v153, v153, 0x3e0293ee, v2
	v_fmamk_f32 v154, v154, 0x3e0293ee, v2
	v_fmamk_f32 v155, v155, 0x3e0293ee, v2
	v_fmamk_f32 v156, v156, 0x3e0293ee, v2
	v_fmamk_f32 v157, v157, 0x3e0293ee, v2
	v_fmamk_f32 v158, v158, 0x3e0293ee, v2
	v_fmac_f32_e32 v2, 0x3e0293ee, v159
	v_exp_f32_e32 v159, v6
	v_exp_f32_e32 v163, v7
	v_exp_f32_e32 v165, v2
	v_add_f32_e32 v2, 0, v3
	v_exp_f32_e32 v8, v8
	v_add_f32_e32 v2, v4, v2
	v_exp_f32_e32 v9, v9
	v_add_f32_e32 v2, v5, v2
	v_exp_f32_e32 v10, v10
	v_add_f32_e32 v2, v159, v2
	v_exp_f32_e32 v11, v11
	v_add_f32_e32 v2, v163, v2
	v_exp_f32_e32 v12, v12
	v_add_f32_e32 v2, v8, v2
	v_exp_f32_e32 v13, v13
	v_add_f32_e32 v2, v9, v2
	v_exp_f32_e32 v164, v14
	v_add_f32_e32 v2, v10, v2
	v_exp_f32_e32 v15, v15
	v_add_f32_e32 v2, v11, v2
	v_exp_f32_e32 v160, v160
	v_add_f32_e32 v2, v12, v2
	v_exp_f32_e32 v161, v161
	v_add_f32_e32 v2, v13, v2
	v_exp_f32_e32 v162, v162
	v_add_f32_e32 v2, v164, v2
	v_exp_f32_e32 v144, v144
	v_add_f32_e32 v2, v15, v2
	v_exp_f32_e32 v145, v145
	v_add_f32_e32 v2, v160, v2
	v_exp_f32_e32 v146, v146
	v_add_f32_e32 v2, v161, v2
	v_exp_f32_e32 v147, v147
	v_add_f32_e32 v2, v162, v2
	v_exp_f32_e32 v148, v148
	v_add_f32_e32 v2, v144, v2
	v_exp_f32_e32 v149, v149
	v_add_f32_e32 v2, v145, v2
	v_exp_f32_e32 v150, v150
	v_add_f32_e32 v2, v146, v2
	v_exp_f32_e32 v151, v151
	v_add_f32_e32 v2, v147, v2
	v_exp_f32_e32 v152, v152
	v_add_f32_e32 v2, v148, v2
	v_exp_f32_e32 v153, v153
	v_add_f32_e32 v2, v149, v2
	v_exp_f32_e32 v154, v154
	v_add_f32_e32 v2, v150, v2
	v_exp_f32_e32 v155, v155
	v_add_f32_e32 v2, v151, v2
	v_exp_f32_e32 v156, v156
	v_add_f32_e32 v2, v152, v2
	v_exp_f32_e32 v157, v157
	v_add_f32_e32 v2, v153, v2
	v_exp_f32_e32 v158, v158
	v_add_f32_e32 v2, v154, v2
	v_add_f32_e32 v2, v155, v2
	v_add_f32_e32 v2, v156, v2
	v_add_f32_e32 v2, v157, v2
	v_add_f32_e32 v2, v158, v2
	v_add_f32_e32 v2, v165, v2
	v_mov_b32_e32 v6, v2
	s_nop 1
	v_permlane32_swap_b32_e32 v2, v6
	v_add_f32_e32 v14, v2, v6
	v_fmac_f32_e32 v14, v250, v0
	v_cvt_pk_bf16_f32 v6, v3, v4
	v_cvt_pk_bf16_f32 v7, v5, v159
	v_cvt_pk_bf16_f32 v8, v163, v8
	v_cvt_pk_bf16_f32 v9, v9, v10
	v_cvt_pk_bf16_f32 v10, v11, v12
	v_cvt_pk_bf16_f32 v11, v13, v164
	v_cvt_pk_bf16_f32 v12, v15, v160
	v_cvt_pk_bf16_f32 v13, v161, v162
	v_cvt_pk_bf16_f32 v144, v144, v145
	v_cvt_pk_bf16_f32 v145, v146, v147
	v_cvt_pk_bf16_f32 v146, v148, v149
	v_cvt_pk_bf16_f32 v147, v150, v151
	v_cvt_pk_bf16_f32 v2, v152, v153
	v_cvt_pk_bf16_f32 v3, v154, v155
	v_cvt_pk_bf16_f32 v4, v156, v157
	v_cvt_pk_bf16_f32 v5, v158, v165
	s_nop 0
	v_permlane32_swap_b32_e32 v6, v8
	v_permlane32_swap_b32_e32 v7, v9
	v_permlane32_swap_b32_e32 v10, v12
	v_permlane32_swap_b32_e32 v11, v13
	v_permlane32_swap_b32_e32 v144, v146
	v_permlane32_swap_b32_e32 v145, v147
	v_permlane32_swap_b32_e32 v2, v4
	v_permlane32_swap_b32_e32 v3, v5
	v_lshl_add_u32 v0, s95, 15, v246
	ds_read_b64_tr_b16 v[148:149], v0 offset:0
	ds_read_b64_tr_b16 v[150:151], v0 offset:0x800
	ds_read_b64_tr_b16 v[152:153], v0 offset:0x4000
	ds_read_b64_tr_b16 v[154:155], v0 offset:0x4800
	ds_read_b64_tr_b16 v[156:157], v0 offset:0x1000
	ds_read_b64_tr_b16 v[158:159], v0 offset:0x1800
	ds_read_b64_tr_b16 v[160:161], v0 offset:0x5000
	ds_read_b64_tr_b16 v[162:163], v0 offset:0x5800
	ds_read_b64_tr_b16 v[164:165], v0 offset:0x2000
	ds_read_b64_tr_b16 v[166:167], v0 offset:0x2800
	ds_read_b64_tr_b16 v[168:169], v0 offset:0x6000
	ds_read_b64_tr_b16 v[170:171], v0 offset:0x6800
	ds_read_b64_tr_b16 v[172:173], v0 offset:0x3000
	ds_read_b64_tr_b16 v[174:175], v0 offset:0x3800
	ds_read_b64_tr_b16 v[176:177], v0 offset:0x7000
	ds_read_b64_tr_b16 v[178:179], v0 offset:0x7800
	s_waitcnt lgkmcnt(0)
; #define A3_BAR() do { asm volatile("s_waitcnt vmcnt(0) lgkmcnt(0)" ::: "memory"); __builtin_amdgcn_s_barrier(); asm volatile("" ::: "memory"); } while (0)
; __device__ __forceinline__ void pv_tile2(f32x16* o, f32x16* o2, int vb0, bf16x8 pa0, bf16x8 pa1, bf16x8 pa2, bf16x8 pa3) {
;     ...
;     PV2_D0(0); PV2_D0(1); PV2_D0(2); PV2_D0(3);
; __device__ __forceinline__ void attn_block3(const BlockRef& cur, char* lds, const int wid) {
;     ...
;         pv_tile2(o, o2, vbase + (t & 1) * 2 * SHM_V, pa0, pa1, pa2, pa3);
;         A3_BAR();
	s_nop 0
	v_mfma_f32_32x32x16_bf16 v[112:127], v[6:9], v[148:151], v[112:127]
	ds_read_b64_tr_b16 v[148:149], v0 offset:0x200
	ds_read_b64_tr_b16 v[150:151], v0 offset:0xa00
	v_mfma_f32_32x32x16_bf16 v[128:143], v[6:9], v[152:155], v[128:143]
	ds_read_b64_tr_b16 v[152:153], v0 offset:0x4200
	ds_read_b64_tr_b16 v[154:155], v0 offset:0x4a00
	v_mfma_f32_32x32x16_bf16 v[112:127], v[10:13], v[156:159], v[112:127]
	ds_read_b64_tr_b16 v[156:157], v0 offset:0x1200
	ds_read_b64_tr_b16 v[158:159], v0 offset:0x1a00
	v_mfma_f32_32x32x16_bf16 v[128:143], v[10:13], v[160:163], v[128:143]
	ds_read_b64_tr_b16 v[160:161], v0 offset:0x5200
	ds_read_b64_tr_b16 v[162:163], v0 offset:0x5a00
	v_mfma_f32_32x32x16_bf16 v[112:127], v[144:147], v[164:167], v[112:127]
	ds_read_b64_tr_b16 v[164:165], v0 offset:0x2200
	ds_read_b64_tr_b16 v[166:167], v0 offset:0x2a00
	v_mfma_f32_32x32x16_bf16 v[128:143], v[144:147], v[168:171], v[128:143]
	ds_read_b64_tr_b16 v[168:169], v0 offset:0x6200
	ds_read_b64_tr_b16 v[170:171], v0 offset:0x6a00
	v_mfma_f32_32x32x16_bf16 v[112:127], v[2:5], v[172:175], v[112:127]
	ds_read_b64_tr_b16 v[172:173], v0 offset:0x3200
	ds_read_b64_tr_b16 v[174:175], v0 offset:0x3a00
	v_mfma_f32_32x32x16_bf16 v[128:143], v[2:5], v[176:179], v[128:143]
	ds_read_b64_tr_b16 v[176:177], v0 offset:0x7200
	ds_read_b64_tr_b16 v[178:179], v0 offset:0x7a00
	s_waitcnt lgkmcnt(0)
	v_mfma_f32_32x32x16_bf16 v[80:95], v[6:9], v[148:151], v[80:95]
	ds_read_b64_tr_b16 v[148:149], v0 offset:0x400
	ds_read_b64_tr_b16 v[150:151], v0 offset:0xc00
	v_mfma_f32_32x32x16_bf16 v[96:111], v[6:9], v[152:155], v[96:111]
	ds_read_b64_tr_b16 v[152:153], v0 offset:0x4400
	ds_read_b64_tr_b16 v[154:155], v0 offset:0x4c00
	v_mfma_f32_32x32x16_bf16 v[80:95], v[10:13], v[156:159], v[80:95]
	ds_read_b64_tr_b16 v[156:157], v0 offset:0x1400
	ds_read_b64_tr_b16 v[158:159], v0 offset:0x1c00
	v_mfma_f32_32x32x16_bf16 v[96:111], v[10:13], v[160:163], v[96:111]
	ds_read_b64_tr_b16 v[160:161], v0 offset:0x5400
	ds_read_b64_tr_b16 v[162:163], v0 offset:0x5c00
	v_mfma_f32_32x32x16_bf16 v[80:95], v[144:147], v[164:167], v[80:95]
	ds_read_b64_tr_b16 v[164:165], v0 offset:0x2400
	ds_read_b64_tr_b16 v[166:167], v0 offset:0x2c00
	v_mfma_f32_32x32x16_bf16 v[96:111], v[144:147], v[168:171], v[96:111]
	ds_read_b64_tr_b16 v[168:169], v0 offset:0x6400
	ds_read_b64_tr_b16 v[170:171], v0 offset:0x6c00
	v_mfma_f32_32x32x16_bf16 v[80:95], v[2:5], v[172:175], v[80:95]
	ds_read_b64_tr_b16 v[172:173], v0 offset:0x3400
	ds_read_b64_tr_b16 v[174:175], v0 offset:0x3c00
	v_mfma_f32_32x32x16_bf16 v[96:111], v[2:5], v[176:179], v[96:111]
	ds_read_b64_tr_b16 v[176:177], v0 offset:0x7400
	ds_read_b64_tr_b16 v[178:179], v0 offset:0x7c00
	s_waitcnt lgkmcnt(0)
	v_mfma_f32_32x32x16_bf16 v[48:63], v[6:9], v[148:151], v[48:63]
	ds_read_b64_tr_b16 v[148:149], v0 offset:0x600
	ds_read_b64_tr_b16 v[150:151], v0 offset:0xe00
	v_mfma_f32_32x32x16_bf16 v[64:79], v[6:9], v[152:155], v[64:79]
	ds_read_b64_tr_b16 v[152:153], v0 offset:0x4600
	ds_read_b64_tr_b16 v[154:155], v0 offset:0x4e00
	v_mfma_f32_32x32x16_bf16 v[48:63], v[10:13], v[156:159], v[48:63]
	ds_read_b64_tr_b16 v[156:157], v0 offset:0x1600
	ds_read_b64_tr_b16 v[158:159], v0 offset:0x1e00
	v_mfma_f32_32x32x16_bf16 v[64:79], v[10:13], v[160:163], v[64:79]
	ds_read_b64_tr_b16 v[160:161], v0 offset:0x5600
	ds_read_b64_tr_b16 v[162:163], v0 offset:0x5e00
	v_mfma_f32_32x32x16_bf16 v[48:63], v[144:147], v[164:167], v[48:63]
	ds_read_b64_tr_b16 v[164:165], v0 offset:0x2600
	ds_read_b64_tr_b16 v[166:167], v0 offset:0x2e00
	v_mfma_f32_32x32x16_bf16 v[64:79], v[144:147], v[168:171], v[64:79]
	ds_read_b64_tr_b16 v[168:169], v0 offset:0x6600
	ds_read_b64_tr_b16 v[170:171], v0 offset:0x6e00
	v_mfma_f32_32x32x16_bf16 v[48:63], v[2:5], v[172:175], v[48:63]
	ds_read_b64_tr_b16 v[172:173], v0 offset:0x3600
	ds_read_b64_tr_b16 v[174:175], v0 offset:0x3e00
	v_mfma_f32_32x32x16_bf16 v[64:79], v[2:5], v[176:179], v[64:79]
	ds_read_b64_tr_b16 v[176:177], v0 offset:0x7600
	ds_read_b64_tr_b16 v[178:179], v0 offset:0x7e00
	s_waitcnt lgkmcnt(0)
	v_mfma_f32_32x32x16_bf16 v[16:31], v[6:9], v[148:151], v[16:31]
	s_waitcnt vmcnt(0) lgkmcnt(0)
	s_barrier
	s_add_u32 s68, s68, 0x4000
	s_addc_u32 s69, s69, 0
	s_add_u32 s98, s98, 0x4000
	s_addc_u32 s99, s99, 0
	s_add_u32 s100, s100, 0x4000
	s_addc_u32 s101, s101, 0
	s_add_i32 s90, s90, 64
	v_add_u32_e32 v247, 0xffffff00, v247
	v_mfma_f32_32x32x16_bf16 v[32:47], v[6:9], v[152:155], v[32:47]
	v_subrev_u32_e32 v248, 64, v248
	s_cmp_eq_u32 s88, s93
	v_mfma_f32_32x32x16_bf16 v[16:31], v[10:13], v[156:159], v[16:31]
	v_mfma_f32_32x32x16_bf16 v[32:47], v[10:13], v[160:163], v[32:47]
	v_mfma_f32_32x32x16_bf16 v[16:31], v[144:147], v[164:167], v[16:31]
	v_mfma_f32_32x32x16_bf16 v[32:47], v[144:147], v[168:171], v[32:47]
	v_mfma_f32_32x32x16_bf16 v[16:31], v[2:5], v[172:175], v[16:31]
	v_mfma_f32_32x32x16_bf16 v[32:47], v[2:5], v[176:179], v[32:47]
	s_cbranch_scc1 .LBB0_491
	v_mov_b32_e32 v250, v14
	s_branch .LBB0_449

; __global__ void __launch_bounds__(512, 2) mega_fwd(Args args) {
	.amdhsa_kernel _Z8mega_fwd4Args
		.amdhsa_group_segment_fixed_size 0
		.amdhsa_private_segment_fixed_size 0
		.amdhsa_kernarg_size 456
		.amdhsa_user_sgpr_count 2
		.amdhsa_user_sgpr_dispatch_ptr 0
		.amdhsa_user_sgpr_queue_ptr 0
		.amdhsa_user_sgpr_kernarg_segment_ptr 1
		.amdhsa_user_sgpr_dispatch_id 0
		.amdhsa_user_sgpr_kernarg_preload_length 0
		.amdhsa_user_sgpr_kernarg_preload_offset 0
		.amdhsa_user_sgpr_private_segment_size 0
		.amdhsa_uses_dynamic_stack 0
		.amdhsa_enable_private_segment 0
		.amdhsa_system_sgpr_workgroup_id_x 1
		.amdhsa_system_sgpr_workgroup_id_y 0
		.amdhsa_system_sgpr_workgroup_id_z 0
		.amdhsa_system_sgpr_workgroup_info 0
		.amdhsa_system_vgpr_workitem_id 2
		.amdhsa_next_free_vgpr 256
		.amdhsa_next_free_sgpr 102
		.amdhsa_accum_offset 256
		.amdhsa_reserve_vcc 1
		.amdhsa_float_round_mode_32 0
		.amdhsa_float_round_mode_16_64 0
		.amdhsa_float_denorm_mode_32 3
		.amdhsa_float_denorm_mode_16_64 3
		.amdhsa_dx10_clamp 1
		.amdhsa_ieee_mode 1
		.amdhsa_fp16_overflow 0
		.amdhsa_tg_split 0
		.amdhsa_exception_fp_ieee_invalid_op 0
		.amdhsa_exception_fp_denorm_src 0
		.amdhsa_exception_fp_ieee_div_zero 0
		.amdhsa_exception_fp_ieee_overflow 0
		.amdhsa_exception_fp_ieee_underflow 0
		.amdhsa_exception_fp_ieee_inexact 0
		.amdhsa_exception_int_div_zero 0
	.end_amdhsa_kernel

; __global__ void __launch_bounds__(512, 2) mega_fwd(Args args) {
amdhsa.kernels:
  - .agpr_count:     0
    .args:
      - .offset:         0
        .size:           200
        .value_kind:     by_value
      - .offset:         200
        .size:           4
        .value_kind:     hidden_block_count_x
      - .offset:         204
        .size:           4
        .value_kind:     hidden_block_count_y
      - .offset:         208
        .size:           4
        .value_kind:     hidden_block_count_z
      - .offset:         212
        .size:           2
        .value_kind:     hidden_group_size_x
      - .offset:         214
        .size:           2
        .value_kind:     hidden_group_size_y
      - .offset:         216
        .size:           2
        .value_kind:     hidden_group_size_z
      - .offset:         218
        .size:           2
        .value_kind:     hidden_remainder_x
      - .offset:         220
        .size:           2
        .value_kind:     hidden_remainder_y
      - .offset:         222
        .size:           2
        .value_kind:     hidden_remainder_z
      - .offset:         240
        .size:           8
        .value_kind:     hidden_global_offset_x
      - .offset:         248
        .size:           8
        .value_kind:     hidden_global_offset_y
      - .offset:         256
        .size:           8
        .value_kind:     hidden_global_offset_z
      - .offset:         264
        .size:           2
        .value_kind:     hidden_grid_dims
      - .offset:         288
        .size:           8
        .value_kind:     hidden_multigrid_sync_arg
      - .offset:         320
        .size:           4
        .value_kind:     hidden_dynamic_lds_size
    .group_segment_fixed_size: 0
    .kernarg_segment_align: 8
    .kernarg_segment_size: 456
    .language:       OpenCL C
    .language_version:
      - 2
      - 0
    .max_flat_workgroup_size: 512
    .name:           _Z8mega_fwd4Args
    .private_segment_fixed_size: 0
    .sgpr_count:     108
    .sgpr_spill_count: 65
    .symbol:         _Z8mega_fwd4Args.kd
    .uniform_work_group_size: 1
    .uses_dynamic_stack: false
    .vgpr_count:     256
    .vgpr_spill_count: 0
    .wavefront_size: 64
